# v90: v88 + XCD-local seam after layer 0 down-projection (layer 1 in-projection reads only same-XCD rows)
# speedup vs baseline: 1.0027x; 1.0012x over previous
; __device__ __forceinline__ unsigned xb_add(unsigned* p, unsigned v) { return __hip_atomic_fetch_add(p, v, __ATOMIC_RELAXED, __HIP_MEMORY_SCOPE_AGENT); }
; __device__ __forceinline__ void xcd_barrier(const XcdBarrier& b) {
;     ...
;     if (threadIdx.x == 0) {
;         unsigned* bar = b.bar;
;         __builtin_amdgcn_s_waitcnt(0);
;         unsigned nloc = b.st[0], nx = b.st[1];
;         if (nloc == 0u) { xcd_barrier_complete(bar, b.x, nloc, nx); b.st[0] = nloc; b.st[1] = nx; }
;         const unsigned old = xb_add(&bar[XB_XSUB(b.x)], 1u);
;         const unsigned gen = old / nloc;
;         if (old + 1u == (gen + 1u) * nloc) {
;             __builtin_amdgcn_fence(__ATOMIC_RELEASE, "agent");
;             asm volatile("s_waitcnt vmcnt(0)" ::: "memory");
;             const unsigned og = xb_add(&bar[XB_TOP], 1u);
;             const unsigned tg = og / nx;
;             if (og + 1u == (tg + 1u) * nx) xb_add(&bar[XB_TOPGEN], 1u);
.LBB0_817:
	s_andn2_saveexec_b64 s[0:1], s[8:9]
	s_cbranch_execz .LBB0_268
	s_mov_b64 s[8:9], exec
	s_waitcnt lgkmcnt(0)
	s_cmp_eq_u32 s71, 0
	s_cbranch_scc1 .Lxloc_down
	buffer_wbl2 sc1
	s_waitcnt lgkmcnt(0)
	s_waitcnt vmcnt(0)
	v_mbcnt_lo_u32_b32 v3, s8, 0
	v_mbcnt_hi_u32_b32 v3, s9, v3
	v_cmp_eq_u32_e32 vcc, 0, v3
	s_and_saveexec_b64 s[10:11], vcc
	s_cbranch_execz .LBB0_820
	s_bcnt1_i32_b64 s0, s[8:9]
	v_mov_b32_e32 v4, s0
	v_mov_b32_e32 v5, 0x7000
	global_atomic_add v4, v5, v4, s[4:5] offset:1024 sc0

; __device__ __forceinline__ unsigned xb_add(unsigned* p, unsigned v) { return __hip_atomic_fetch_add(p, v, __ATOMIC_RELAXED, __HIP_MEMORY_SCOPE_AGENT); }
; __device__ __forceinline__ void xcd_barrier(const XcdBarrier& b) {
;     ...
;             __builtin_amdgcn_fence(__ATOMIC_ACQUIRE, "agent");
;             xb_add(&bar[XB_XGEN(b.x)], 1u);
;             asm volatile("s_waitcnt vmcnt(0)" ::: "memory");
.Lxloc_down:
	s_mov_b64 s[4:5], exec
	v_mbcnt_lo_u32_b32 v2, s4, 0
	v_mbcnt_hi_u32_b32 v2, s5, v2
	v_cmp_eq_u32_e32 vcc, 0, v2
	s_waitcnt vmcnt(0)
	buffer_inv sc1
	s_and_saveexec_b64 s[8:9], vcc
	s_cbranch_execz .LBB0_267
	s_bcnt1_i32_b64 s0, s[4:5]
	v_mov_b32_e32 v2, s0
	v_mov_b32_e32 v3, 0x2000
	global_atomic_add v3, v2, s[6:7] offset:1024
	s_branch .LBB0_267
